# baseline (speedup 1.0000x reference)
; DI void cmp_item(const u16* R, const u16* kc, const u16* vct, float* Oc, float* impH, float* linv, int hh, int qtile, float kcmax2, int part, float* lds) {
;     ...
;   const int ntiles = ((t0 >> 4) >> 5) + 1;
;   const int cnear = (tq - 31) >> 4;
;   const float bnear = -slope * ((float)(tq - 16 * cnear) - 15.5f);
;   const float mshift = sqrtf(q_norm2(q) * kcmax2) * 1.02f + 0.01f + (cnear >= 0 ? bnear : 0.f);
;   AState st; state_init(st);
;   float carryE = 0.f, l = 0.f;
;   float* imp_row = impH + ((size_t)hh * SEQ + tq) * 256;
;   const int hsplit = (ntiles + 1) >> 1;
;   const int kbeg = part ? hsplit : 0, kend = part ? ntiles : hsplit;
;   if (part && kbeg < kend) {
;     KV wkv;
;     const int n0 = 32 * (kbeg - 1);
;     load_kv<false, false>(wkv, f, n0, nullptr);
;     f32x16 s = qk_tile(wkv, q);
;     const int c = n0 + 8 * h2 + 7 + 16;
;     const bool valid = (16 * c + 31) <= tq;
;     const float p15 = valid ? __expf(s[15] - slope * ((float)(tq - 16 * c) - 15.5f) - mshift) : 0.f;
;     carryE = __shfl_xor(p15, 32);
;   }
;   if (kbeg < kend) {
;     KV cur, nxt;
;     load_kv<true, false>(cur, f, 32 * kbeg, nullptr);
;     nxt = cur;
;     for (int k = kbeg; k < kend; ++k) {
.LBB0_870:
	s_or_b64 exec, exec, s[30:31]
	s_lshl_b32 s2, s54, 14
	v_mov_b32_e32 v17, 0
	s_xor_b64 s[30:31], s[46:47], -1
	v_and_b32_e32 v143, 63, v18
	s_lshl_b32 s55, s54, 6
	v_lshl_add_u64 v[128:129], v[126:127], 0, s[2:3]
	v_mov_b32_e32 v16, v17
	v_mov_b32_e32 v15, v17
	v_mov_b32_e32 v14, v17
	v_mov_b32_e32 v13, v17
	v_mov_b32_e32 v12, v17
	v_mov_b32_e32 v11, v17
	v_mov_b32_e32 v10, v17
	v_mov_b32_e32 v9, v17
	v_mov_b32_e32 v8, v17
	v_mov_b32_e32 v7, v17
	v_mov_b32_e32 v6, v17
	v_mov_b32_e32 v5, v17
	v_mov_b32_e32 v4, v17
	v_mov_b32_e32 v3, v17
	v_mov_b32_e32 v2, v17
	v_mov_b32_e32 v33, v17
	v_mov_b32_e32 v32, v17
	v_mov_b32_e32 v31, v17
	v_mov_b32_e32 v30, v17
	v_mov_b32_e32 v29, v17
	v_mov_b32_e32 v28, v17
	v_mov_b32_e32 v27, v17
	v_mov_b32_e32 v26, v17
	v_mov_b32_e32 v25, v17
	v_mov_b32_e32 v24, v17
	v_mov_b32_e32 v23, v17
	v_mov_b32_e32 v22, v17
	v_mov_b32_e32 v21, v17
	v_mov_b32_e32 v20, v17
	v_mov_b32_e32 v19, v17
	v_mov_b32_e32 v18, v17
	v_mov_b32_e32 v145, v17
	s_and_saveexec_b64 s[48:49], vcc
	s_cbranch_execz .LBB0_906
	v_readlane_b32 s10, v252, 52
	v_lshlrev_b32_e32 v0, 11, v38
	v_readlane_b32 s11, v252, 53
	v_mov_b32_e32 v4, v159
	v_lshlrev_b64 v[2:3], 10, v[128:129]
	v_lshl_add_u64 v[130:131], s[10:11], 0, v[0:1]
	v_lshl_add_u64 v[132:133], s[0:1], 0, v[2:3]
	v_and_b32_e32 v208, 32, v159
	v_lshrrev_b32_e32 v208, 2, v208
	v_mov_b32_e32 v209, 0
	v_lshl_add_u64 v[132:133], v[132:133], 0, v[208:209]
	v_lshlrev_b32_e32 v0, 1, v4
	v_and_b32_e32 v0, 8, v0
	v_lshrrev_b32_e32 v2, 1, v4
	v_lshlrev_b32_e32 v6, 5, v142
	v_and_b32_e32 v2, 4, v2
	v_and_or_b32 v0, v4, 19, v0
	v_or3_b32 v0, v0, v2, v6
	v_max_i32_e32 v0, 0, v0
	v_lshlrev_b64 v[2:3], 7, v[0:1]
	v_lshrrev_b32_e32 v0, 2, v4
	v_and_b32_e32 v4, 8, v0
	v_lshl_add_u64 v[2:3], s[36:37], 0, v[2:3]
	v_lshlrev_b32_e32 v0, 1, v4
	v_or_b32_e32 v4, v4, v6
	v_lshl_add_u64 v[2:3], v[2:3], 0, v[0:1]
	v_max_i32_e32 v0, 0, v4
	v_lshlrev_b32_e32 v0, 1, v0
	global_load_dwordx4 v[34:37], v[2:3], off
	global_load_dwordx4 v[114:117], v[2:3], off offset:32
	global_load_dwordx4 v[122:125], v[2:3], off offset:64
	global_load_dwordx4 v[118:121], v[2:3], off offset:96
	v_lshl_add_u64 v[2:3], v[130:131], 0, v[0:1]
	global_load_dwordx4 v[78:81], v[2:3], off
	v_or_b32_e32 v2, 16, v4
	v_max_i32_e32 v2, 0, v2
	s_mov_b64 s[10:11], 0x10000
	v_lshlrev_b32_e32 v2, 1, v2
	v_mov_b32_e32 v3, v1
	v_lshl_add_u64 v[134:135], v[130:131], 0, s[10:11]
	v_lshl_add_u64 v[4:5], v[130:131], 0, v[2:3]
	v_lshl_add_u64 v[2:3], v[134:135], 0, v[2:3]
	global_load_dwordx4 v[74:77], v[4:5], off
	global_load_dwordx4 v[66:69], v[2:3], off
	v_lshl_add_u64 v[4:5], v[134:135], 0, v[0:1]
	global_load_dwordx4 v[70:73], v[4:5], off
	s_add_i32 s2, s76, 0xfffffe90
	v_lshlrev_b32_e32 v2, 7, v139
	v_add_u32_e32 v3, s2, v38
	v_lshlrev_b32_e32 v0, 1, v139
	v_sub_u32_e32 v3, v3, v2
	v_lshlrev_b32_e32 v4, 9, v142
	s_movk_i32 s2, 0x11f
	v_mov_b32_e32 v145, 0
	v_cmp_gt_u32_e32 vcc, 32, v143
	v_sub_u32_e32 v146, v3, v4
	v_or3_b32 v147, v4, v2, s2
	v_lshl_or_b32 v136, v142, 3, v0
	v_add_u32_e32 v148, 32, v6
	s_mov_b64 s[50:51], 0
	v_mov_b32_e32 v2, 0
	v_mov_b32_e32 v3, v145
	v_mov_b32_e32 v4, v145
	v_mov_b32_e32 v5, v145
	v_mov_b32_e32 v6, v145
	v_mov_b32_e32 v7, v145
	v_mov_b32_e32 v8, v145
	v_mov_b32_e32 v9, v145
	v_mov_b32_e32 v10, v145
	v_mov_b32_e32 v11, v145
	v_mov_b32_e32 v12, v145
	v_mov_b32_e32 v13, v145
	v_mov_b32_e32 v14, v145
	v_mov_b32_e32 v15, v145
	v_mov_b32_e32 v16, v145
	v_mov_b32_e32 v17, v145
	v_mov_b32_e32 v18, 0
	v_mov_b32_e32 v19, v145
	v_mov_b32_e32 v20, v145
	v_mov_b32_e32 v21, v145
	v_mov_b32_e32 v22, v145
	v_mov_b32_e32 v23, v145
	v_mov_b32_e32 v24, v145
	v_mov_b32_e32 v25, v145
	v_mov_b32_e32 v26, v145
	v_mov_b32_e32 v27, v145
	v_mov_b32_e32 v28, v145
	v_mov_b32_e32 v29, v145
	v_mov_b32_e32 v30, v145
	v_mov_b32_e32 v31, v145
	v_mov_b32_e32 v32, v145
	v_mov_b32_e32 v33, v145
	s_waitcnt vmcnt(7)
	v_mov_b64_e32 v[112:113], v[36:37]
	s_waitcnt vmcnt(6)
	v_mov_b64_e32 v[106:107], v[114:115]
	s_waitcnt vmcnt(5)
	v_mov_b64_e32 v[102:103], v[122:123]
	s_waitcnt vmcnt(4)
	v_mov_b64_e32 v[98:99], v[118:119]
	v_mov_b64_e32 v[100:101], v[120:121]
	s_waitcnt vmcnt(3)
	v_mov_b64_e32 v[88:89], v[80:81]
	v_mov_b64_e32 v[86:87], v[78:79]
	v_mov_b64_e32 v[104:105], v[124:125]
	v_mov_b64_e32 v[108:109], v[116:117]
	v_mov_b64_e32 v[110:111], v[34:35]
	s_waitcnt vmcnt(2)
	v_mov_b64_e32 v[84:85], v[76:77]
	s_waitcnt vmcnt(1)
	v_mov_b64_e32 v[92:93], v[68:69]
	v_mov_b64_e32 v[90:91], v[66:67]
	s_waitcnt vmcnt(0)
	v_mov_b64_e32 v[96:97], v[72:73]
	v_mov_b64_e32 v[94:95], v[70:71]
	v_mov_b64_e32 v[82:83], v[74:75]
	s_branch .LBB0_873
; DI void cmp_item(const u16* R, const u16* kc, const u16* vct, float* Oc, float* impH, float* linv, int hh, int qtile, float kcmax2, int part, float* lds) {
;     ...
;       const float g0 = p[0] + p[1] + p[2] + p[3], g1 = p[4] + p[5] + p[6] + p[7];
;       const float g2 = p[8] + p[9] + p[10] + p[11], g3 = p[12] + p[13] + p[14] + p[15];
;       l += (g0 + g1) + (g2 + g3);
;       const float xp7 = __shfl_xor(p[7], 32), xp15 = __shfl_xor(p[15], 32);
;       const int gb = (n0 >> 2) + 2 * h2;
;       f32x2 w0 = {g0 + (h2 ? xp7 : carryE), g1 + p[3]};
;       f32x2 w1 = {g2 + (h2 ? xp15 : xp7), g3 + p[11]};
;       *reinterpret_cast<f32x2*>(imp_row + gb) = w0;
;       *reinterpret_cast<f32x2*>(imp_row + gb + 4) = w1;
;       carryE = xp15;
;       pv_tile(cur, p, st);
;       cur = nxt;
.LBB0_872:
	s_or_b64 exec, exec, s[52:53]
	v_add_u32_e32 v40, 0x170, v146
	v_cvt_f32_i32_e32 v40, v40
	v_add_u32_e32 v0, 0xffffff00, v147
	s_and_b64 s[10:11], exec, s[44:45]
	v_cmp_le_i32_e64 s[44:45], v0, v126
	v_add_f32_e32 v40, 0xc1780000, v40
	v_fma_f32 v34, -v140, v40, v34
	v_sub_f32_e32 v34, v34, v141
	v_mul_f32_e32 v34, 0x3fb8aa3b, v34
	v_exp_f32_e32 v34, v34
	v_pk_add_f32 v[42:43], v[120:121], v[36:37]
	ds_bpermute_b32 v48, v138, v39
	v_pk_add_f32 v[42:43], v[42:43], v[122:123]
	v_cndmask_b32_e64 v34, 0, v34, s[44:45]
	v_pk_add_f32 v[40:41], v[34:35], v[116:117]
	v_pk_add_f32 v[42:43], v[42:43], v[38:39]
	v_pk_add_f32 v[40:41], v[40:41], v[118:119]
	v_mov_b32_e32 v47, v42
	v_pk_add_f32 v[40:41], v[40:41], v[114:115]
	s_or_b64 s[50:51], s[10:11], s[50:51]
	v_pk_add_f32 v[44:45], v[40:41], v[42:43]
	v_mov_b32_e32 v46, v40
	v_add_f32_e32 v0, v44, v45
	v_add_f32_e32 v145, v145, v0
	ds_bpermute_b32 v0, v138, v38
	v_mov_b32_e32 v45, v114
	v_mov_b32_e32 v42, v41
	v_mov_b32_e32 v41, v115
	v_add_u32_e32 v146, 0xfffffe00, v146
	s_waitcnt lgkmcnt(0)
	v_cndmask_b32_e32 v44, v0, v137, vcc
	v_cndmask_b32_e32 v40, v48, v0, vcc
	v_ashrrev_i32_e32 v137, 31, v136
	v_pk_add_f32 v[204:205], v[46:47], v[44:45]
	v_pk_add_f32 v[206:207], v[42:43], v[40:41]
	v_lshl_add_u64 v[42:43], v[136:137], 2, v[132:133]
	s_nop 0
	v_permlane32_swap_b32_e32 v204, v206
	v_permlane32_swap_b32_e32 v205, v207
	global_store_dwordx4 v[42:43], v[204:207], off
	v_cvt_pk_bf16_f32 v40, v34, v116
	v_cvt_pk_bf16_f32 v41, v118, v114
	v_cvt_pk_bf16_f32 v42, v120, v36
	v_cvt_pk_bf16_f32 v43, v122, v38
	v_cvt_pk_bf16_f32 v34, v35, v117
	v_cvt_pk_bf16_f32 v35, v119, v115
	v_mfma_f32_32x32x16_bf16 v[18:33], v[78:81], v[40:43], v[18:33]
	v_cvt_pk_bf16_f32 v36, v121, v37
	v_cvt_pk_bf16_f32 v37, v123, v39
	s_waitcnt vmcnt(7)
	v_mov_b64_e32 v[116:117], v[108:109]
	s_waitcnt vmcnt(6)
	v_mov_b64_e32 v[124:125], v[104:105]
	s_waitcnt vmcnt(5)
	v_mov_b64_e32 v[120:121], v[100:101]
	s_waitcnt vmcnt(4)
	v_mov_b64_e32 v[78:79], v[86:87]
	v_add_u32_e32 v147, 0x200, v147
	v_mfma_f32_32x32x16_bf16 v[2:17], v[70:73], v[40:43], v[2:17]
	s_waitcnt vmcnt(2)
	v_mov_b64_e32 v[70:71], v[94:95]
	v_add_u32_e32 v136, 8, v136
	v_add_u32_e32 v148, 32, v148
	v_mov_b32_e32 v137, v48
	v_mov_b64_e32 v[114:115], v[106:107]
	v_mov_b64_e32 v[122:123], v[102:103]
	v_mov_b64_e32 v[118:119], v[98:99]
	v_mfma_f32_32x32x16_bf16 v[18:33], v[74:77], v[34:37], v[18:33]
	v_mov_b64_e32 v[74:75], v[82:83]
	v_mov_b64_e32 v[80:81], v[88:89]
	v_mov_b64_e32 v[76:77], v[84:85]
	v_mov_b64_e32 v[72:73], v[96:97]
	v_mfma_f32_32x32x16_bf16 v[2:17], v[66:69], v[34:37], v[2:17]
	v_mov_b64_e32 v[34:35], v[110:111]
	s_waitcnt vmcnt(1)
	v_mov_b64_e32 v[66:67], v[90:91]
	v_mov_b64_e32 v[36:37], v[112:113]
	v_mov_b64_e32 v[68:69], v[92:93]
	s_andn2_b64 exec, exec, s[50:51]
	s_cbranch_execz .LBB0_905
